# V-transposed scatter stores packed in token pairs (EpiKV and EpiMemKV): 2-byte stores halved into dword stores
# speedup vs baseline: 1.0162x; 1.0069x over previous
.LBB0_1851:
	v_mbcnt_lo_u32_b32 v237, -1, 0
	v_mbcnt_hi_u32_b32 v237, -1, v237
	v_and_b32_e32 v237, 1, v237
	v_mul_u32_u24_e32 v232, 0x1fe, v237
	v_mov_b32_e32 v233, 0
	v_mov_b32_e32 v236, 0x7060302
	v_mov_b32_e32 v238, 0x3020706
	v_cmp_ne_u32_e32 vcc, 0, v237
	s_nop 1
	v_cndmask_b32_e32 v236, v236, v238, vcc
	s_lshl_b32 s28, s53, 8
	s_add_i32 s28, s28, s46
	s_ashr_i32 s29, s28, 6
	s_and_b32 s29, s29, -4
	s_add_i32 s56, s29, s51
	s_lshl_b32 s26, s51, 7
	s_ashr_i32 s57, s56, 31
	s_ashr_i32 s27, s26, 31
	v_or_b32_e32 v156, s28, v142
	s_lshl_b64 s[56:57], s[56:57], 16
	v_ashrrev_i32_e32 v157, 31, v156
	v_cvt_pk_bf16_f32 v124, v124, v125
	v_cvt_pk_bf16_f32 v125, v126, v127
	v_cvt_pk_bf16_f32 v126, v120, v121
	v_lshlrev_b64 v[120:121], 10, v[156:157]
	v_lshl_add_u64 v[120:121], s[14:15], 0, v[120:121]
	s_lshl_b64 s[26:27], s[26:27], 1
	v_lshl_add_u64 v[120:121], v[120:121], 0, s[26:27]
	v_cvt_pk_bf16_f32 v127, v122, v123
	v_lshl_add_u64 v[120:121], v[120:121], 0, v[144:145]
	v_bitop3_b32 v122, s28, v184, v142 bitop3:0xc8
	flat_store_dwordx4 v[120:121], v[124:127]
	v_lshl_add_u64 v[120:121], v[136:137], 0, s[56:57]
	v_lshlrev_b32_e32 v122, 1, v122
	v_mov_b32_e32 v123, v145
	v_lshl_add_u64 v[122:123], v[120:121], 0, v[122:123]
	v_cmp_ne_u32_e32 vcc, 0, v237
	v_bfe_u32 v238, v104, 16, 1
	v_add3_u32 v104, v104, v238, s1
	v_bfe_u32 v238, v105, 16, 1
	v_add3_u32 v105, v105, v238, s1
	v_bfe_u32 v238, v106, 16, 1
	v_add3_u32 v106, v106, v238, s1
	v_bfe_u32 v238, v107, 16, 1
	v_add3_u32 v107, v107, v238, s1
	v_bfe_u32 v238, v116, 16, 1
	v_add3_u32 v116, v116, v238, s1
	v_bfe_u32 v238, v117, 16, 1
	v_add3_u32 v117, v117, v238, s1
	v_bfe_u32 v238, v118, 16, 1
	v_add3_u32 v118, v118, v238, s1
	v_bfe_u32 v238, v119, 16, 1
	v_add3_u32 v119, v119, v238, s1
	v_cndmask_b32_e32 v220, v104, v105, vcc
	v_cndmask_b32_e32 v224, v105, v104, vcc
	v_cndmask_b32_e32 v221, v106, v107, vcc
	v_cndmask_b32_e32 v225, v107, v106, vcc
	v_cndmask_b32_e32 v222, v116, v117, vcc
	v_cndmask_b32_e32 v226, v117, v116, vcc
	v_cndmask_b32_e32 v223, v118, v119, vcc
	v_cndmask_b32_e32 v227, v119, v118, vcc
	v_lshl_add_u64 v[228:229], v[122:123], 0, v[232:233]
	v_mov_b32_dpp v224, v224 quad_perm:[1,0,3,2] row_mask:0xf bank_mask:0xf
	v_mov_b32_dpp v225, v225 quad_perm:[1,0,3,2] row_mask:0xf bank_mask:0xf
	v_mov_b32_dpp v226, v226 quad_perm:[1,0,3,2] row_mask:0xf bank_mask:0xf
	v_mov_b32_dpp v227, v227 quad_perm:[1,0,3,2] row_mask:0xf bank_mask:0xf
	s_nop 0
	v_perm_b32 v220, v224, v220, v236
	global_store_dword v[228:229], v220, off
	v_perm_b32 v221, v225, v221, v236
	global_store_dword v[228:229], v221, off offset:1024
	v_perm_b32 v222, v226, v222, v236
	global_store_dword v[228:229], v222, off offset:2048
	v_perm_b32 v223, v227, v223, v236
	global_store_dword v[228:229], v223, off offset:3072
	v_or_b32_e32 v116, 16, v156
	v_ashrrev_i32_e32 v117, 31, v116
	v_cvt_pk_bf16_f32 v106, v108, v109
	v_lshlrev_b64 v[108:109], 10, v[116:117]
	v_lshl_add_u64 v[108:109], s[14:15], 0, v[108:109]
	v_lshl_add_u64 v[108:109], v[108:109], 0, s[26:27]
	v_cvt_pk_bf16_f32 v104, v112, v113
	v_cvt_pk_bf16_f32 v105, v114, v115
	v_cvt_pk_bf16_f32 v107, v110, v111
	v_lshl_add_u64 v[108:109], v[108:109], 0, v[144:145]
	s_movk_i32 s56, 0xdf
	flat_store_dwordx4 v[108:109], v[104:107]
	s_nop 1
	v_bitop3_b32 v104, v156, s56, 16 bitop3:0xc8
	v_lshlrev_b32_e32 v104, 1, v104
	v_mov_b32_e32 v105, v145
	v_lshl_add_u64 v[104:105], v[120:121], 0, v[104:105]
	v_cmp_ne_u32_e32 vcc, 0, v237
	v_bfe_u32 v238, v100, 16, 1
	v_add3_u32 v100, v100, v238, s1
	v_bfe_u32 v238, v101, 16, 1
	v_add3_u32 v101, v101, v238, s1
	v_bfe_u32 v238, v102, 16, 1
	v_add3_u32 v102, v102, v238, s1
	v_bfe_u32 v238, v103, 16, 1
	v_add3_u32 v103, v103, v238, s1
	v_bfe_u32 v238, v96, 16, 1
	v_add3_u32 v96, v96, v238, s1
	v_bfe_u32 v238, v97, 16, 1
	v_add3_u32 v97, v97, v238, s1
	v_bfe_u32 v238, v98, 16, 1
	v_add3_u32 v98, v98, v238, s1
	v_bfe_u32 v238, v99, 16, 1
	v_add3_u32 v99, v99, v238, s1
	v_cndmask_b32_e32 v220, v100, v101, vcc
	v_cndmask_b32_e32 v224, v101, v100, vcc
	v_cndmask_b32_e32 v221, v102, v103, vcc
	v_cndmask_b32_e32 v225, v103, v102, vcc
	v_cndmask_b32_e32 v222, v96, v97, vcc
	v_cndmask_b32_e32 v226, v97, v96, vcc
	v_cndmask_b32_e32 v223, v98, v99, vcc
	v_cndmask_b32_e32 v227, v99, v98, vcc
	v_lshl_add_u64 v[228:229], v[104:105], 0, v[232:233]
	v_mov_b32_dpp v224, v224 quad_perm:[1,0,3,2] row_mask:0xf bank_mask:0xf
	v_mov_b32_dpp v225, v225 quad_perm:[1,0,3,2] row_mask:0xf bank_mask:0xf
	v_mov_b32_dpp v226, v226 quad_perm:[1,0,3,2] row_mask:0xf bank_mask:0xf
	v_mov_b32_dpp v227, v227 quad_perm:[1,0,3,2] row_mask:0xf bank_mask:0xf
	s_nop 0
	v_perm_b32 v220, v224, v220, v236
	global_store_dword v[228:229], v220, off
	v_perm_b32 v221, v225, v221, v236
	global_store_dword v[228:229], v221, off offset:1024
	v_perm_b32 v222, v226, v222, v236
	global_store_dword v[228:229], v222, off offset:2048
	v_perm_b32 v223, v227, v223, v236
	global_store_dword v[228:229], v223, off offset:3072
	v_or_b32_e32 v96, 32, v156
	v_ashrrev_i32_e32 v97, 31, v96
	v_cvt_pk_bf16_f32 v92, v92, v93
	v_cvt_pk_bf16_f32 v93, v94, v95
	v_cvt_pk_bf16_f32 v94, v88, v89
	v_lshlrev_b64 v[88:89], 10, v[96:97]
	v_lshl_add_u64 v[88:89], s[14:15], 0, v[88:89]
	v_lshl_add_u64 v[88:89], v[88:89], 0, s[26:27]
	v_cvt_pk_bf16_f32 v95, v90, v91
	v_lshl_add_u64 v[88:89], v[88:89], 0, v[144:145]
	s_movk_i32 s57, 0xef
	flat_store_dwordx4 v[88:89], v[92:95]
	v_bitop3_b32 v88, v156, s57, 32 bitop3:0xc8
	v_lshlrev_b32_e32 v88, 1, v88
	v_mov_b32_e32 v89, v145
	v_lshl_add_u64 v[88:89], v[120:121], 0, v[88:89]
	v_cmp_ne_u32_e32 vcc, 0, v237
	v_bfe_u32 v238, v84, 16, 1
	v_add3_u32 v84, v84, v238, s1
; __device__ __forceinline__ unsigned f2bf(float f) { unsigned u = __builtin_bit_cast(unsigned, f); return (u + 0x7fffu + ((u >> 16) & 1u)) >> 16; }
	v_bfe_u32 v238, v85, 16, 1
	v_add3_u32 v85, v85, v238, s1
	v_bfe_u32 v238, v86, 16, 1
	v_add3_u32 v86, v86, v238, s1
	v_bfe_u32 v238, v87, 16, 1
	v_add3_u32 v87, v87, v238, s1
	v_bfe_u32 v238, v80, 16, 1
	v_add3_u32 v80, v80, v238, s1
	v_bfe_u32 v238, v81, 16, 1
	v_add3_u32 v81, v81, v238, s1
	v_bfe_u32 v238, v82, 16, 1
	v_add3_u32 v82, v82, v238, s1
	v_bfe_u32 v238, v83, 16, 1
	v_add3_u32 v83, v83, v238, s1
	v_cndmask_b32_e32 v220, v84, v85, vcc
	v_cndmask_b32_e32 v224, v85, v84, vcc
	v_cndmask_b32_e32 v221, v86, v87, vcc
	v_cndmask_b32_e32 v225, v87, v86, vcc
	v_cndmask_b32_e32 v222, v80, v81, vcc
	v_cndmask_b32_e32 v226, v81, v80, vcc
	v_cndmask_b32_e32 v223, v82, v83, vcc
	v_cndmask_b32_e32 v227, v83, v82, vcc
	v_lshl_add_u64 v[228:229], v[88:89], 0, v[232:233]
	v_mov_b32_dpp v224, v224 quad_perm:[1,0,3,2] row_mask:0xf bank_mask:0xf
	v_mov_b32_dpp v225, v225 quad_perm:[1,0,3,2] row_mask:0xf bank_mask:0xf
	v_mov_b32_dpp v226, v226 quad_perm:[1,0,3,2] row_mask:0xf bank_mask:0xf
	v_mov_b32_dpp v227, v227 quad_perm:[1,0,3,2] row_mask:0xf bank_mask:0xf
	s_nop 0
	v_perm_b32 v220, v224, v220, v236
	global_store_dword v[228:229], v220, off
	v_perm_b32 v221, v225, v221, v236
	global_store_dword v[228:229], v221, off offset:1024
	v_perm_b32 v222, v226, v222, v236
	global_store_dword v[228:229], v222, off offset:2048
	v_perm_b32 v223, v227, v223, v236
	global_store_dword v[228:229], v223, off offset:3072
	v_or_b32_e32 v80, 48, v156
	v_ashrrev_i32_e32 v81, 31, v80
	v_cvt_pk_bf16_f32 v76, v76, v77
	v_cvt_pk_bf16_f32 v77, v78, v79
	v_cvt_pk_bf16_f32 v78, v72, v73
	v_lshlrev_b64 v[72:73], 10, v[80:81]
	v_lshl_add_u64 v[72:73], s[14:15], 0, v[72:73]
	v_lshl_add_u64 v[72:73], v[72:73], 0, s[26:27]
	v_cvt_pk_bf16_f32 v79, v74, v75
	v_lshl_add_u64 v[72:73], v[72:73], 0, v[144:145]
	s_movk_i32 s53, 0xff
	flat_store_dwordx4 v[72:73], v[76:79]
	v_bitop3_b32 v72, v156, s53, 48 bitop3:0xc8
	v_lshlrev_b32_e32 v72, 1, v72
	v_mov_b32_e32 v73, v145
	v_lshl_add_u64 v[72:73], v[120:121], 0, v[72:73]
	s_add_i32 s33, s28, 0x80
	s_ashr_i32 s28, s33, 6
	s_and_b32 s28, s28, -4
	s_add_i32 s28, s28, s51
	s_ashr_i32 s29, s28, 31
	v_cmp_ne_u32_e32 vcc, 0, v237
	v_bfe_u32 v238, v68, 16, 1
	v_add3_u32 v68, v68, v238, s1
	v_bfe_u32 v238, v69, 16, 1
	v_add3_u32 v69, v69, v238, s1
	v_bfe_u32 v238, v70, 16, 1
	v_add3_u32 v70, v70, v238, s1
	v_bfe_u32 v238, v71, 16, 1
	v_add3_u32 v71, v71, v238, s1
	v_bfe_u32 v238, v64, 16, 1
	v_add3_u32 v64, v64, v238, s1
	v_bfe_u32 v238, v65, 16, 1
	v_add3_u32 v65, v65, v238, s1
	v_bfe_u32 v238, v66, 16, 1
	v_add3_u32 v66, v66, v238, s1
	v_bfe_u32 v238, v67, 16, 1
	v_add3_u32 v67, v67, v238, s1
	v_cndmask_b32_e32 v220, v68, v69, vcc
	v_cndmask_b32_e32 v224, v69, v68, vcc
	v_cndmask_b32_e32 v221, v70, v71, vcc
	v_cndmask_b32_e32 v225, v71, v70, vcc
	v_cndmask_b32_e32 v222, v64, v65, vcc
	v_cndmask_b32_e32 v226, v65, v64, vcc
	v_cndmask_b32_e32 v223, v66, v67, vcc
	v_cndmask_b32_e32 v227, v67, v66, vcc
	v_lshl_add_u64 v[228:229], v[72:73], 0, v[232:233]
	v_mov_b32_dpp v224, v224 quad_perm:[1,0,3,2] row_mask:0xf bank_mask:0xf
	v_mov_b32_dpp v225, v225 quad_perm:[1,0,3,2] row_mask:0xf bank_mask:0xf
	v_mov_b32_dpp v226, v226 quad_perm:[1,0,3,2] row_mask:0xf bank_mask:0xf
	v_mov_b32_dpp v227, v227 quad_perm:[1,0,3,2] row_mask:0xf bank_mask:0xf
	s_nop 0
	v_perm_b32 v220, v224, v220, v236
	global_store_dword v[228:229], v220, off
	v_perm_b32 v221, v225, v221, v236
	global_store_dword v[228:229], v221, off offset:1024
	v_perm_b32 v222, v226, v222, v236
	global_store_dword v[228:229], v222, off offset:2048
	v_perm_b32 v223, v227, v223, v236
	global_store_dword v[228:229], v223, off offset:3072
	v_or_b32_e32 v64, s33, v142
	s_lshl_b64 s[28:29], s[28:29], 16
	v_ashrrev_i32_e32 v65, 31, v64
	v_cvt_pk_bf16_f32 v60, v60, v61
	v_cvt_pk_bf16_f32 v61, v62, v63
	v_cvt_pk_bf16_f32 v62, v56, v57
	v_lshlrev_b64 v[56:57], 10, v[64:65]
	v_lshl_add_u64 v[56:57], s[14:15], 0, v[56:57]
	v_lshl_add_u64 v[56:57], v[56:57], 0, s[26:27]
	v_cvt_pk_bf16_f32 v63, v58, v59
	v_lshl_add_u64 v[56:57], v[56:57], 0, v[144:145]
	v_bitop3_b32 v58, s33, v184, v142 bitop3:0xc8
	flat_store_dwordx4 v[56:57], v[60:63]
	v_lshl_add_u64 v[56:57], v[136:137], 0, s[28:29]
	v_lshlrev_b32_e32 v58, 1, v58
	v_mov_b32_e32 v59, v145
	v_lshl_add_u64 v[58:59], v[56:57], 0, v[58:59]
	v_cmp_ne_u32_e32 vcc, 0, v237
	v_bfe_u32 v238, v52, 16, 1
	v_add3_u32 v52, v52, v238, s1
	v_bfe_u32 v238, v53, 16, 1
	v_add3_u32 v53, v53, v238, s1
	v_bfe_u32 v238, v54, 16, 1
	v_add3_u32 v54, v54, v238, s1
	v_bfe_u32 v238, v55, 16, 1
	v_add3_u32 v55, v55, v238, s1
	v_bfe_u32 v238, v48, 16, 1
	v_add3_u32 v48, v48, v238, s1
	v_bfe_u32 v238, v49, 16, 1
	v_add3_u32 v49, v49, v238, s1
	v_bfe_u32 v238, v50, 16, 1
	v_add3_u32 v50, v50, v238, s1
	v_bfe_u32 v238, v51, 16, 1
	v_add3_u32 v51, v51, v238, s1
	v_cndmask_b32_e32 v220, v52, v53, vcc
	v_cndmask_b32_e32 v224, v53, v52, vcc
	v_cndmask_b32_e32 v221, v54, v55, vcc
	v_cndmask_b32_e32 v225, v55, v54, vcc
	v_cndmask_b32_e32 v222, v48, v49, vcc
	v_cndmask_b32_e32 v226, v49, v48, vcc
	v_cndmask_b32_e32 v223, v50, v51, vcc
	v_cndmask_b32_e32 v227, v51, v50, vcc
	v_lshl_add_u64 v[228:229], v[58:59], 0, v[232:233]
	v_mov_b32_dpp v224, v224 quad_perm:[1,0,3,2] row_mask:0xf bank_mask:0xf
	v_mov_b32_dpp v225, v225 quad_perm:[1,0,3,2] row_mask:0xf bank_mask:0xf
	v_mov_b32_dpp v226, v226 quad_perm:[1,0,3,2] row_mask:0xf bank_mask:0xf
	v_mov_b32_dpp v227, v227 quad_perm:[1,0,3,2] row_mask:0xf bank_mask:0xf
	s_nop 0
	v_perm_b32 v220, v224, v220, v236
	global_store_dword v[228:229], v220, off
	v_perm_b32 v221, v225, v221, v236
	global_store_dword v[228:229], v221, off offset:1024
; __device__ __forceinline__ unsigned f2bf(float f) { unsigned u = __builtin_bit_cast(unsigned, f); return (u + 0x7fffu + ((u >> 16) & 1u)) >> 16; }
	v_perm_b32 v222, v226, v222, v236
	global_store_dword v[228:229], v222, off offset:2048
	v_perm_b32 v223, v227, v223, v236
	global_store_dword v[228:229], v223, off offset:3072
	v_or_b32_e32 v48, 16, v64
	v_ashrrev_i32_e32 v49, 31, v48
	v_cvt_pk_bf16_f32 v44, v44, v45
	v_cvt_pk_bf16_f32 v45, v46, v47
	v_cvt_pk_bf16_f32 v46, v40, v41
	v_lshlrev_b64 v[40:41], 10, v[48:49]
	v_lshl_add_u64 v[40:41], s[14:15], 0, v[40:41]
	v_lshl_add_u64 v[40:41], v[40:41], 0, s[26:27]
	v_cvt_pk_bf16_f32 v47, v42, v43
	v_lshl_add_u64 v[40:41], v[40:41], 0, v[144:145]
	flat_store_dwordx4 v[40:41], v[44:47]
	v_bitop3_b32 v40, v64, s56, 16 bitop3:0xc8
	v_lshlrev_b32_e32 v40, 1, v40
	v_mov_b32_e32 v41, v145
	v_lshl_add_u64 v[40:41], v[56:57], 0, v[40:41]
	v_cmp_ne_u32_e32 vcc, 0, v237
	v_bfe_u32 v238, v36, 16, 1
	v_add3_u32 v36, v36, v238, s1
	v_bfe_u32 v238, v37, 16, 1
	v_add3_u32 v37, v37, v238, s1
	v_bfe_u32 v238, v38, 16, 1
	v_add3_u32 v38, v38, v238, s1
	v_bfe_u32 v238, v39, 16, 1
	v_add3_u32 v39, v39, v238, s1
	v_bfe_u32 v238, v32, 16, 1
	v_add3_u32 v32, v32, v238, s1
	v_bfe_u32 v238, v33, 16, 1
	v_add3_u32 v33, v33, v238, s1
	v_bfe_u32 v238, v34, 16, 1
	v_add3_u32 v34, v34, v238, s1
	v_bfe_u32 v238, v35, 16, 1
	v_add3_u32 v35, v35, v238, s1
	v_cndmask_b32_e32 v220, v36, v37, vcc
	v_cndmask_b32_e32 v224, v37, v36, vcc
	v_cndmask_b32_e32 v221, v38, v39, vcc
	v_cndmask_b32_e32 v225, v39, v38, vcc
	v_cndmask_b32_e32 v222, v32, v33, vcc
	v_cndmask_b32_e32 v226, v33, v32, vcc
	v_cndmask_b32_e32 v223, v34, v35, vcc
	v_cndmask_b32_e32 v227, v35, v34, vcc
	v_lshl_add_u64 v[228:229], v[40:41], 0, v[232:233]
	v_mov_b32_dpp v224, v224 quad_perm:[1,0,3,2] row_mask:0xf bank_mask:0xf
	v_mov_b32_dpp v225, v225 quad_perm:[1,0,3,2] row_mask:0xf bank_mask:0xf
	v_mov_b32_dpp v226, v226 quad_perm:[1,0,3,2] row_mask:0xf bank_mask:0xf
	v_mov_b32_dpp v227, v227 quad_perm:[1,0,3,2] row_mask:0xf bank_mask:0xf
	s_nop 0
	v_perm_b32 v220, v224, v220, v236
	global_store_dword v[228:229], v220, off
	v_perm_b32 v221, v225, v221, v236
	global_store_dword v[228:229], v221, off offset:1024
	v_perm_b32 v222, v226, v222, v236
	global_store_dword v[228:229], v222, off offset:2048
	v_perm_b32 v223, v227, v223, v236
	global_store_dword v[228:229], v223, off offset:3072
	v_or_b32_e32 v32, 32, v64
	v_ashrrev_i32_e32 v33, 31, v32
	v_cvt_pk_bf16_f32 v28, v28, v29
	v_cvt_pk_bf16_f32 v29, v30, v31
	v_cvt_pk_bf16_f32 v30, v24, v25
	v_lshlrev_b64 v[24:25], 10, v[32:33]
	v_lshl_add_u64 v[24:25], s[14:15], 0, v[24:25]
	v_lshl_add_u64 v[24:25], v[24:25], 0, s[26:27]
	v_cvt_pk_bf16_f32 v31, v26, v27
	v_lshl_add_u64 v[24:25], v[24:25], 0, v[144:145]
	flat_store_dwordx4 v[24:25], v[28:31]
	v_bitop3_b32 v24, v64, s57, 32 bitop3:0xc8
	v_lshlrev_b32_e32 v24, 1, v24
	v_mov_b32_e32 v25, v145
	v_lshl_add_u64 v[24:25], v[56:57], 0, v[24:25]
	v_cmp_ne_u32_e32 vcc, 0, v237
	v_bfe_u32 v238, v20, 16, 1
	v_add3_u32 v20, v20, v238, s1
	v_bfe_u32 v238, v21, 16, 1
	v_add3_u32 v21, v21, v238, s1
	v_bfe_u32 v238, v22, 16, 1
	v_add3_u32 v22, v22, v238, s1
	v_bfe_u32 v238, v23, 16, 1
	v_add3_u32 v23, v23, v238, s1
	v_bfe_u32 v238, v16, 16, 1
	v_add3_u32 v16, v16, v238, s1
	v_bfe_u32 v238, v17, 16, 1
	v_add3_u32 v17, v17, v238, s1
	v_bfe_u32 v238, v18, 16, 1
	v_add3_u32 v18, v18, v238, s1
	v_bfe_u32 v238, v19, 16, 1
	v_add3_u32 v19, v19, v238, s1
	v_cndmask_b32_e32 v220, v20, v21, vcc
	v_cndmask_b32_e32 v224, v21, v20, vcc
	v_cndmask_b32_e32 v221, v22, v23, vcc
	v_cndmask_b32_e32 v225, v23, v22, vcc
	v_cndmask_b32_e32 v222, v16, v17, vcc
	v_cndmask_b32_e32 v226, v17, v16, vcc
	v_cndmask_b32_e32 v223, v18, v19, vcc
	v_cndmask_b32_e32 v227, v19, v18, vcc
	v_lshl_add_u64 v[228:229], v[24:25], 0, v[232:233]
	v_mov_b32_dpp v224, v224 quad_perm:[1,0,3,2] row_mask:0xf bank_mask:0xf
	v_mov_b32_dpp v225, v225 quad_perm:[1,0,3,2] row_mask:0xf bank_mask:0xf
	v_mov_b32_dpp v226, v226 quad_perm:[1,0,3,2] row_mask:0xf bank_mask:0xf
	v_mov_b32_dpp v227, v227 quad_perm:[1,0,3,2] row_mask:0xf bank_mask:0xf
	s_nop 0
	v_perm_b32 v220, v224, v220, v236
	global_store_dword v[228:229], v220, off
	v_perm_b32 v221, v225, v221, v236
	global_store_dword v[228:229], v221, off offset:1024
	v_perm_b32 v222, v226, v222, v236
	global_store_dword v[228:229], v222, off offset:2048
	v_perm_b32 v223, v227, v223, v236
	global_store_dword v[228:229], v223, off offset:3072
	v_or_b32_e32 v16, 48, v64
	v_ashrrev_i32_e32 v17, 31, v16
	v_cvt_pk_bf16_f32 v12, v12, v13
	v_cvt_pk_bf16_f32 v13, v14, v15
	v_cvt_pk_bf16_f32 v14, v8, v9
	v_lshlrev_b64 v[8:9], 10, v[16:17]
	v_lshl_add_u64 v[8:9], s[14:15], 0, v[8:9]
	v_lshl_add_u64 v[8:9], v[8:9], 0, s[26:27]
	v_cvt_pk_bf16_f32 v15, v10, v11
	v_lshl_add_u64 v[8:9], v[8:9], 0, v[144:145]
	flat_store_dwordx4 v[8:9], v[12:15]
	v_bitop3_b32 v8, v64, s53, 48 bitop3:0xc8
	v_lshlrev_b32_e32 v8, 1, v8
	v_mov_b32_e32 v9, v145
	v_lshl_add_u64 v[8:9], v[56:57], 0, v[8:9]
	v_cmp_ne_u32_e32 vcc, 0, v237
	v_bfe_u32 v238, v4, 16, 1
	v_add3_u32 v4, v4, v238, s1
	v_bfe_u32 v238, v5, 16, 1
	v_add3_u32 v5, v5, v238, s1
	v_bfe_u32 v238, v6, 16, 1
	v_add3_u32 v6, v6, v238, s1
	v_bfe_u32 v238, v7, 16, 1
	v_add3_u32 v7, v7, v238, s1
	v_bfe_u32 v238, v0, 16, 1
	v_add3_u32 v0, v0, v238, s1
	v_bfe_u32 v238, v1, 16, 1
	v_add3_u32 v1, v1, v238, s1
	v_bfe_u32 v238, v2, 16, 1
	v_add3_u32 v2, v2, v238, s1
	v_bfe_u32 v238, v3, 16, 1
	v_add3_u32 v3, v3, v238, s1
	v_cndmask_b32_e32 v220, v4, v5, vcc
	v_cndmask_b32_e32 v224, v5, v4, vcc
	v_cndmask_b32_e32 v221, v6, v7, vcc
	v_cndmask_b32_e32 v225, v7, v6, vcc
	v_cndmask_b32_e32 v222, v0, v1, vcc
	v_cndmask_b32_e32 v226, v1, v0, vcc
	v_cndmask_b32_e32 v223, v2, v3, vcc
	v_cndmask_b32_e32 v227, v3, v2, vcc
	v_lshl_add_u64 v[228:229], v[8:9], 0, v[232:233]
	v_mov_b32_dpp v224, v224 quad_perm:[1,0,3,2] row_mask:0xf bank_mask:0xf
	v_mov_b32_dpp v225, v225 quad_perm:[1,0,3,2] row_mask:0xf bank_mask:0xf
	v_mov_b32_dpp v226, v226 quad_perm:[1,0,3,2] row_mask:0xf bank_mask:0xf
	v_mov_b32_dpp v227, v227 quad_perm:[1,0,3,2] row_mask:0xf bank_mask:0xf
	s_nop 0
	v_perm_b32 v220, v224, v220, v236
	global_store_dword v[228:229], v220, off
	v_perm_b32 v221, v225, v221, v236
	global_store_dword v[228:229], v221, off offset:1024
	v_perm_b32 v222, v226, v222, v236
	global_store_dword v[228:229], v222, off offset:2048
	v_perm_b32 v223, v227, v223, v236
	global_store_dword v[228:229], v223, off offset:3072
	s_and_b64 vcc, exec, s[2:3]
	s_mov_b64 s[2:3], -1
	s_cbranch_vccnz .LBB0_1834
	s_andn2_b64 vcc, exec, s[12:13]
	s_cbranch_vccnz .LBB0_1833
	s_barrier
	s_branch .LBB0_1833
